# selected-branch softmax: (score - max) subtractions packed two per instruction (7 packed + 1 scalar per tile, identical arithmetic)
# baseline (speedup 1.0000x reference)
.LBB0_630:
	v_mov_b32_e32 v132, v219
	s_nop 1
	v_permlane16_swap_b32_e32 v219, v132
	v_max_f32_e32 v132, v132, v132
	v_max_f32_e32 v133, v219, v219
	v_max_f32_e32 v132, v133, v132
	v_mov_b32_e32 v133, v132
	s_nop 1
	v_permlane32_swap_b32_e32 v132, v133
	v_max3_f32 v219, v218, v132, v133
	v_cndmask_b32_e64 v132, 0, 1, s[20:21]
	v_cmp_ne_u32_e64 s[10:11], 1, v132
	v_pk_add_f32 v[134:135], v[30:31], v[218:219] op_sel:[0,1] op_sel_hi:[1,1] neg_lo:[0,1] neg_hi:[0,1]
	v_pk_add_f32 v[142:143], v[174:175], v[218:219] op_sel:[0,1] op_sel_hi:[1,1] neg_lo:[0,1] neg_hi:[0,1]
	v_pk_add_f32 v[140:141], v[176:177], v[218:219] op_sel:[0,1] op_sel_hi:[1,1] neg_lo:[0,1] neg_hi:[0,1]
	v_pk_add_f32 v[138:139], v[180:181], v[218:219] op_sel:[0,1] op_sel_hi:[1,1] neg_lo:[0,1] neg_hi:[0,1]
	v_pk_add_f32 v[136:137], v[182:183], v[218:219] op_sel:[0,1] op_sel_hi:[1,1] neg_lo:[0,1] neg_hi:[0,1]
	v_pk_add_f32 v[222:223], v[184:185], v[218:219] op_sel:[0,1] op_sel_hi:[1,1] neg_lo:[0,1] neg_hi:[0,1]
	v_pk_add_f32 v[224:225], v[186:187], v[218:219] op_sel:[0,1] op_sel_hi:[1,1] neg_lo:[0,1] neg_hi:[0,1]
	v_sub_f32_e32 v226, v178, v219
	s_mov_b64 s[2:3], -1
	s_andn2_b64 vcc, exec, s[20:21]
	v_mul_f32_e32 v146, 0x3fb8aa3b, v134
	v_mul_f32_e32 v145, 0x3fb8aa3b, v135
	v_mul_f32_e32 v144, 0x3fb8aa3b, v142
	v_mul_f32_e32 v143, 0x3fb8aa3b, v143
	v_mul_f32_e32 v142, 0x3fb8aa3b, v140
	v_mul_f32_e32 v141, 0x3fb8aa3b, v141
	v_mul_f32_e32 v140, 0x3fb8aa3b, v138
	v_mul_f32_e32 v139, 0x3fb8aa3b, v139
	v_mul_f32_e32 v138, 0x3fb8aa3b, v136
	v_mul_f32_e32 v137, 0x3fb8aa3b, v137
	v_mul_f32_e32 v136, 0x3fb8aa3b, v222
	v_mul_f32_e32 v135, 0x3fb8aa3b, v223
	v_mul_f32_e32 v134, 0x3fb8aa3b, v224
	v_mul_f32_e32 v133, 0x3fb8aa3b, v225
	v_mul_f32_e32 v132, 0x3fb8aa3b, v226
	s_cbranch_vccnz .LBB0_632
	v_cmp_lt_f32_e32 vcc, s51, v30
	v_exp_f32_e32 v30, v146
	v_cmp_lt_f32_e64 s[0:1], s51, v179
	s_mov_b64 s[2:3], 0
	v_cndmask_b32_e32 v221, 0, v30, vcc
	v_cmp_lt_f32_e32 vcc, s51, v31
	v_exp_f32_e32 v31, v145
	v_add_f32_e32 v30, 0, v221
	v_cndmask_b32_e32 v222, 0, v31, vcc
	v_exp_f32_e32 v31, v144
	v_cmp_lt_f32_e32 vcc, s51, v174
	v_add_f32_e32 v30, v222, v30
	s_nop 0
	v_cndmask_b32_e32 v223, 0, v31, vcc
	v_exp_f32_e32 v31, v143
	v_cmp_lt_f32_e32 vcc, s51, v175
	v_add_f32_e32 v30, v223, v30
	s_nop 0
	v_cndmask_b32_e32 v224, 0, v31, vcc
	v_exp_f32_e32 v31, v142
	v_cmp_lt_f32_e32 vcc, s51, v176
	v_add_f32_e32 v30, v224, v30
	s_nop 0
	v_cndmask_b32_e32 v225, 0, v31, vcc
	v_exp_f32_e32 v31, v141
	v_cmp_lt_f32_e32 vcc, s51, v177
	v_add_f32_e32 v30, v225, v30
	s_nop 0
	v_cndmask_b32_e32 v227, 0, v31, vcc
	v_exp_f32_e32 v31, v140
	v_cmp_lt_f32_e32 vcc, s51, v180
	v_add_f32_e32 v30, v227, v30
	s_nop 0
	v_cndmask_b32_e32 v229, 0, v31, vcc
	v_exp_f32_e32 v31, v139
	v_cmp_lt_f32_e32 vcc, s51, v181
	v_add_f32_e32 v30, v229, v30
	s_nop 0
	v_cndmask_b32_e32 v231, 0, v31, vcc
	v_exp_f32_e32 v31, v138
	v_cmp_lt_f32_e32 vcc, s51, v182
	v_add_f32_e32 v30, v231, v30
	s_nop 0
	v_cndmask_b32_e32 v226, 0, v31, vcc
	v_exp_f32_e32 v31, v137
	v_cmp_lt_f32_e32 vcc, s51, v183
	v_add_f32_e32 v30, v226, v30
	s_nop 0
	v_cndmask_b32_e32 v228, 0, v31, vcc
	v_exp_f32_e32 v31, v136
	v_cmp_lt_f32_e32 vcc, s51, v184
	v_add_f32_e32 v30, v228, v30
	s_nop 0
	v_cndmask_b32_e32 v230, 0, v31, vcc
	v_exp_f32_e32 v31, v135
	v_cmp_lt_f32_e32 vcc, s51, v185
	v_add_f32_e32 v30, v230, v30
	s_nop 0
	v_cndmask_b32_e32 v232, 0, v31, vcc
	v_exp_f32_e32 v31, v134
	v_cmp_lt_f32_e32 vcc, s51, v186
	v_add_f32_e32 v30, v232, v30
	s_nop 0
	v_cndmask_b32_e32 v233, 0, v31, vcc
	v_exp_f32_e32 v31, v133
	v_cmp_lt_f32_e32 vcc, s51, v187
	v_add_f32_e32 v30, v233, v30
	s_nop 0
	v_cndmask_b32_e32 v234, 0, v31, vcc
	v_exp_f32_e32 v31, v132
	v_cmp_lt_f32_e32 vcc, s51, v178
	v_add_f32_e32 v30, v234, v30
	s_nop 0
	v_cndmask_b32_e32 v235, 0, v31, vcc
	v_add_f32_e32 v147, v235, v30

.LBB0_640:
	v_mov_b32_e32 v116, v176
	s_nop 1
	v_permlane16_swap_b32_e32 v176, v116
	v_max_f32_e32 v116, v116, v116
	v_max_f32_e32 v117, v176, v176
	v_max_f32_e32 v116, v117, v116
	v_mov_b32_e32 v117, v116
	s_nop 1
	v_permlane32_swap_b32_e32 v116, v117
	v_max3_f32 v220, v217, v116, v117
	v_pk_add_f32 v[118:119], v[132:133], v[220:221] op_sel_hi:[1,0] neg_lo:[0,1] neg_hi:[0,1]
	v_pk_add_f32 v[120:121], v[134:135], v[220:221] op_sel_hi:[1,0] neg_lo:[0,1] neg_hi:[0,1]
	v_pk_add_f32 v[122:123], v[136:137], v[220:221] op_sel_hi:[1,0] neg_lo:[0,1] neg_hi:[0,1]
	v_pk_add_f32 v[124:125], v[140:141], v[220:221] op_sel_hi:[1,0] neg_lo:[0,1] neg_hi:[0,1]
	v_pk_add_f32 v[130:131], v[142:143], v[220:221] op_sel_hi:[1,0] neg_lo:[0,1] neg_hi:[0,1]
	v_pk_add_f32 v[128:129], v[144:145], v[220:221] op_sel_hi:[1,0] neg_lo:[0,1] neg_hi:[0,1]
	v_pk_add_f32 v[126:127], v[146:147], v[220:221] op_sel_hi:[1,0] neg_lo:[0,1] neg_hi:[0,1]
	v_sub_f32_e32 v187, v138, v220
	s_mov_b64 s[2:3], -1
	s_and_b64 vcc, exec, s[10:11]
	v_mul_f32_e32 v186, 0x3fb8aa3b, v118
	v_mul_f32_e32 v185, 0x3fb8aa3b, v119
	v_mul_f32_e32 v184, 0x3fb8aa3b, v120
	v_mul_f32_e32 v183, 0x3fb8aa3b, v121
	v_mul_f32_e32 v182, 0x3fb8aa3b, v122
	v_mul_f32_e32 v181, 0x3fb8aa3b, v123
	v_mul_f32_e32 v180, 0x3fb8aa3b, v124
	v_mul_f32_e32 v179, 0x3fb8aa3b, v125
	v_mul_f32_e32 v178, 0x3fb8aa3b, v130
	v_mul_f32_e32 v177, 0x3fb8aa3b, v131
	v_mul_f32_e32 v131, 0x3fb8aa3b, v128
	v_mul_f32_e32 v130, 0x3fb8aa3b, v129
	v_mul_f32_e32 v129, 0x3fb8aa3b, v126
	v_mul_f32_e32 v117, 0x3fb8aa3b, v127
	v_mul_f32_e32 v116, 0x3fb8aa3b, v187
	s_cbranch_vccnz .LBB0_642
	v_exp_f32_e32 v118, v186
	v_exp_f32_e32 v119, v185
	v_cmp_lt_f32_e32 vcc, s51, v132
	v_exp_f32_e32 v124, v181
	v_exp_f32_e32 v125, v180
	v_cndmask_b32_e32 v118, 0, v118, vcc
	v_cmp_lt_f32_e32 vcc, s51, v133
	v_add_f32_e32 v120, 0, v118
	v_exp_f32_e32 v133, v130
	v_cndmask_b32_e32 v119, 0, v119, vcc
	v_add_f32_e32 v121, v119, v120
	v_exp_f32_e32 v120, v184
	v_cmp_lt_f32_e32 vcc, s51, v134
	v_cmp_lt_f32_e64 s[0:1], s51, v139
	s_mov_b64 s[2:3], 0
	v_cndmask_b32_e32 v120, 0, v120, vcc
	v_add_f32_e32 v122, v120, v121
	v_exp_f32_e32 v121, v183
	v_cmp_lt_f32_e32 vcc, s51, v135
	s_nop 1
	v_cndmask_b32_e32 v121, 0, v121, vcc
	v_add_f32_e32 v123, v121, v122
	v_exp_f32_e32 v122, v182
	v_cmp_lt_f32_e32 vcc, s51, v136
	s_nop 1
	v_cndmask_b32_e32 v122, 0, v122, vcc
	v_cmp_lt_f32_e32 vcc, s51, v137
	v_add_f32_e32 v123, v122, v123
	s_nop 0
	v_cndmask_b32_e32 v124, 0, v124, vcc
	v_cmp_lt_f32_e32 vcc, s51, v140
	v_add_f32_e32 v123, v124, v123
	s_nop 0
	v_cndmask_b32_e32 v126, 0, v125, vcc
	v_exp_f32_e32 v125, v179
	v_cmp_lt_f32_e32 vcc, s51, v141
	v_add_f32_e32 v123, v126, v123
	s_nop 0
	v_cndmask_b32_e32 v128, 0, v125, vcc
	v_add_f32_e32 v125, v128, v123
	v_exp_f32_e32 v123, v178
	v_cmp_lt_f32_e32 vcc, s51, v142
	s_nop 1
	v_cndmask_b32_e32 v123, 0, v123, vcc
	v_add_f32_e32 v127, v123, v125
	v_exp_f32_e32 v125, v177
	v_cmp_lt_f32_e32 vcc, s51, v143
	s_nop 1
	v_cndmask_b32_e32 v125, 0, v125, vcc
	v_add_f32_e32 v132, v125, v127
	v_exp_f32_e32 v127, v131
	v_cmp_lt_f32_e32 vcc, s51, v144
	s_nop 1
	v_cndmask_b32_e32 v127, 0, v127, vcc
	v_cmp_lt_f32_e32 vcc, s51, v145
	v_add_f32_e32 v132, v127, v132
	s_nop 0
	v_cndmask_b32_e32 v176, 0, v133, vcc
	v_exp_f32_e32 v133, v129
	v_cmp_lt_f32_e32 vcc, s51, v146
	v_add_f32_e32 v132, v176, v132
	s_nop 0
	v_cndmask_b32_e32 v187, 0, v133, vcc
	v_exp_f32_e32 v133, v117
	v_cmp_lt_f32_e32 vcc, s51, v147
	v_add_f32_e32 v132, v187, v132
	s_nop 0
	v_cndmask_b32_e32 v218, 0, v133, vcc
	v_exp_f32_e32 v133, v116
	v_cmp_lt_f32_e32 vcc, s51, v138
	v_add_f32_e32 v132, v218, v132
	s_nop 0
	v_cndmask_b32_e32 v236, 0, v133, vcc
	v_add_f32_e32 v237, v236, v132

.LBB0_658:
	v_mov_b32_e32 v132, v218
	s_nop 1
	v_permlane16_swap_b32_e32 v218, v132
	v_max_f32_e32 v132, v132, v132
	v_max_f32_e32 v133, v218, v218
	v_max_f32_e32 v132, v133, v132
	v_mov_b32_e32 v133, v132
	s_nop 1
	v_permlane32_swap_b32_e32 v132, v133
	v_max3_f32 v218, v219, v132, v133
	v_cndmask_b32_e64 v132, 0, 1, s[18:19]
	v_cmp_ne_u32_e64 s[10:11], 1, v132
	v_pk_add_f32 v[134:135], v[30:31], v[218:219] op_sel_hi:[1,0] neg_lo:[0,1] neg_hi:[0,1]
	v_pk_add_f32 v[142:143], v[174:175], v[218:219] op_sel_hi:[1,0] neg_lo:[0,1] neg_hi:[0,1]
	v_pk_add_f32 v[140:141], v[176:177], v[218:219] op_sel_hi:[1,0] neg_lo:[0,1] neg_hi:[0,1]
	v_pk_add_f32 v[138:139], v[180:181], v[218:219] op_sel_hi:[1,0] neg_lo:[0,1] neg_hi:[0,1]
	v_pk_add_f32 v[136:137], v[182:183], v[218:219] op_sel_hi:[1,0] neg_lo:[0,1] neg_hi:[0,1]
	v_pk_add_f32 v[222:223], v[184:185], v[218:219] op_sel_hi:[1,0] neg_lo:[0,1] neg_hi:[0,1]
	v_pk_add_f32 v[224:225], v[186:187], v[218:219] op_sel_hi:[1,0] neg_lo:[0,1] neg_hi:[0,1]
	v_sub_f32_e32 v226, v178, v218
	s_mov_b64 s[2:3], -1
	s_andn2_b64 vcc, exec, s[18:19]
	v_mul_f32_e32 v146, 0x3fb8aa3b, v134
	v_mul_f32_e32 v145, 0x3fb8aa3b, v135
	v_mul_f32_e32 v144, 0x3fb8aa3b, v142
	v_mul_f32_e32 v143, 0x3fb8aa3b, v143
	v_mul_f32_e32 v142, 0x3fb8aa3b, v140
	v_mul_f32_e32 v141, 0x3fb8aa3b, v141
	v_mul_f32_e32 v140, 0x3fb8aa3b, v138
	v_mul_f32_e32 v139, 0x3fb8aa3b, v139
	v_mul_f32_e32 v138, 0x3fb8aa3b, v136
	v_mul_f32_e32 v137, 0x3fb8aa3b, v137
	v_mul_f32_e32 v136, 0x3fb8aa3b, v222
	v_mul_f32_e32 v135, 0x3fb8aa3b, v223
	v_mul_f32_e32 v134, 0x3fb8aa3b, v224
	v_mul_f32_e32 v133, 0x3fb8aa3b, v225
	v_mul_f32_e32 v132, 0x3fb8aa3b, v226
	s_cbranch_vccnz .LBB0_660
	v_cmp_lt_f32_e32 vcc, s51, v30
	v_exp_f32_e32 v30, v146
	v_cmp_lt_f32_e64 s[0:1], s51, v179
	s_mov_b64 s[2:3], 0
	v_cndmask_b32_e32 v221, 0, v30, vcc
	v_cmp_lt_f32_e32 vcc, s51, v31
	v_exp_f32_e32 v31, v145
	v_add_f32_e32 v30, 0, v221
	v_cndmask_b32_e32 v222, 0, v31, vcc
	v_exp_f32_e32 v31, v144
	v_cmp_lt_f32_e32 vcc, s51, v174
	v_add_f32_e32 v30, v222, v30
	s_nop 0
	v_cndmask_b32_e32 v223, 0, v31, vcc
	v_exp_f32_e32 v31, v143
	v_cmp_lt_f32_e32 vcc, s51, v175
	v_add_f32_e32 v30, v223, v30
	s_nop 0
	v_cndmask_b32_e32 v224, 0, v31, vcc
	v_exp_f32_e32 v31, v142
	v_cmp_lt_f32_e32 vcc, s51, v176
	v_add_f32_e32 v30, v224, v30
	s_nop 0
	v_cndmask_b32_e32 v225, 0, v31, vcc
	v_exp_f32_e32 v31, v141
	v_cmp_lt_f32_e32 vcc, s51, v177
	v_add_f32_e32 v30, v225, v30
	s_nop 0
	v_cndmask_b32_e32 v227, 0, v31, vcc
	v_exp_f32_e32 v31, v140
	v_cmp_lt_f32_e32 vcc, s51, v180
	v_add_f32_e32 v30, v227, v30
	s_nop 0
	v_cndmask_b32_e32 v229, 0, v31, vcc
	v_exp_f32_e32 v31, v139
	v_cmp_lt_f32_e32 vcc, s51, v181
	v_add_f32_e32 v30, v229, v30
	s_nop 0
	v_cndmask_b32_e32 v231, 0, v31, vcc
	v_exp_f32_e32 v31, v138
	v_cmp_lt_f32_e32 vcc, s51, v182
	v_add_f32_e32 v30, v231, v30
	s_nop 0
	v_cndmask_b32_e32 v226, 0, v31, vcc
	v_exp_f32_e32 v31, v137
	v_cmp_lt_f32_e32 vcc, s51, v183
	v_add_f32_e32 v30, v226, v30
	s_nop 0
	v_cndmask_b32_e32 v228, 0, v31, vcc
	v_exp_f32_e32 v31, v136
	v_cmp_lt_f32_e32 vcc, s51, v184
	v_add_f32_e32 v30, v228, v30
	s_nop 0
	v_cndmask_b32_e32 v230, 0, v31, vcc
	v_exp_f32_e32 v31, v135
	v_cmp_lt_f32_e32 vcc, s51, v185
	v_add_f32_e32 v30, v230, v30
	s_nop 0
	v_cndmask_b32_e32 v232, 0, v31, vcc
	v_exp_f32_e32 v31, v134
	v_cmp_lt_f32_e32 vcc, s51, v186
	v_add_f32_e32 v30, v232, v30
	s_nop 0
	v_cndmask_b32_e32 v233, 0, v31, vcc
	v_exp_f32_e32 v31, v133
	v_cmp_lt_f32_e32 vcc, s51, v187
	v_add_f32_e32 v30, v233, v30
	s_nop 0
	v_cndmask_b32_e32 v234, 0, v31, vcc
	v_exp_f32_e32 v31, v132
	v_cmp_lt_f32_e32 vcc, s51, v178
	v_add_f32_e32 v30, v234, v30
	s_nop 0
	v_cndmask_b32_e32 v235, 0, v31, vcc
	v_add_f32_e32 v147, v235, v30

.LBB0_668:
	v_mov_b32_e32 v116, v176
	s_nop 1
	v_permlane16_swap_b32_e32 v176, v116
	v_max_f32_e32 v116, v116, v116
	v_max_f32_e32 v117, v176, v176
	v_max_f32_e32 v116, v117, v116
	v_mov_b32_e32 v117, v116
	s_nop 1
	v_permlane32_swap_b32_e32 v116, v117
	v_max3_f32 v217, v220, v116, v117
	v_pk_add_f32 v[118:119], v[132:133], v[216:217] op_sel:[0,1] op_sel_hi:[1,1] neg_lo:[0,1] neg_hi:[0,1]
	v_pk_add_f32 v[120:121], v[134:135], v[216:217] op_sel:[0,1] op_sel_hi:[1,1] neg_lo:[0,1] neg_hi:[0,1]
	v_pk_add_f32 v[122:123], v[136:137], v[216:217] op_sel:[0,1] op_sel_hi:[1,1] neg_lo:[0,1] neg_hi:[0,1]
	v_pk_add_f32 v[124:125], v[140:141], v[216:217] op_sel:[0,1] op_sel_hi:[1,1] neg_lo:[0,1] neg_hi:[0,1]
	v_pk_add_f32 v[128:129], v[142:143], v[216:217] op_sel:[0,1] op_sel_hi:[1,1] neg_lo:[0,1] neg_hi:[0,1]
	v_pk_add_f32 v[130:131], v[144:145], v[216:217] op_sel:[0,1] op_sel_hi:[1,1] neg_lo:[0,1] neg_hi:[0,1]
	v_pk_add_f32 v[126:127], v[146:147], v[216:217] op_sel:[0,1] op_sel_hi:[1,1] neg_lo:[0,1] neg_hi:[0,1]
	v_sub_f32_e32 v187, v138, v217
	s_mov_b64 s[2:3], -1
	s_and_b64 vcc, exec, s[10:11]
	v_mul_f32_e32 v186, 0x3fb8aa3b, v118
	v_mul_f32_e32 v185, 0x3fb8aa3b, v119
	v_mul_f32_e32 v184, 0x3fb8aa3b, v120
	v_mul_f32_e32 v183, 0x3fb8aa3b, v121
	v_mul_f32_e32 v182, 0x3fb8aa3b, v122
	v_mul_f32_e32 v181, 0x3fb8aa3b, v123
	v_mul_f32_e32 v180, 0x3fb8aa3b, v124
	v_mul_f32_e32 v179, 0x3fb8aa3b, v125
	v_mul_f32_e32 v178, 0x3fb8aa3b, v128
	v_mul_f32_e32 v177, 0x3fb8aa3b, v129
	v_mul_f32_e32 v176, 0x3fb8aa3b, v130
	v_mul_f32_e32 v130, 0x3fb8aa3b, v131
	v_mul_f32_e32 v129, 0x3fb8aa3b, v126
	v_mul_f32_e32 v117, 0x3fb8aa3b, v127
	v_mul_f32_e32 v116, 0x3fb8aa3b, v187
	s_cbranch_vccnz .LBB0_670
	v_exp_f32_e32 v118, v186
	v_exp_f32_e32 v119, v185
	v_cmp_lt_f32_e32 vcc, s51, v132
	v_exp_f32_e32 v124, v181
	v_exp_f32_e32 v125, v180
	v_cndmask_b32_e32 v118, 0, v118, vcc
	v_cmp_lt_f32_e32 vcc, s51, v133
	v_add_f32_e32 v120, 0, v118
	v_exp_f32_e32 v133, v129
	v_cndmask_b32_e32 v119, 0, v119, vcc
	v_add_f32_e32 v121, v119, v120
	v_exp_f32_e32 v120, v184
	v_cmp_lt_f32_e32 vcc, s51, v134
	v_cmp_lt_f32_e64 s[0:1], s51, v139
	s_mov_b64 s[2:3], 0
	v_cndmask_b32_e32 v120, 0, v120, vcc
	v_add_f32_e32 v122, v120, v121
	v_exp_f32_e32 v121, v183
	v_cmp_lt_f32_e32 vcc, s51, v135
	s_nop 1
	v_cndmask_b32_e32 v121, 0, v121, vcc
	v_add_f32_e32 v123, v121, v122
	v_exp_f32_e32 v122, v182
	v_cmp_lt_f32_e32 vcc, s51, v136
	s_nop 1
	v_cndmask_b32_e32 v122, 0, v122, vcc
	v_cmp_lt_f32_e32 vcc, s51, v137
	v_add_f32_e32 v123, v122, v123
	s_nop 0
	v_cndmask_b32_e32 v124, 0, v124, vcc
	v_cmp_lt_f32_e32 vcc, s51, v140
	v_add_f32_e32 v123, v124, v123
	s_nop 0
	v_cndmask_b32_e32 v126, 0, v125, vcc
	v_exp_f32_e32 v125, v179
	v_cmp_lt_f32_e32 vcc, s51, v141
	v_add_f32_e32 v123, v126, v123
	s_nop 0
	v_cndmask_b32_e32 v128, 0, v125, vcc
	v_add_f32_e32 v125, v128, v123
	v_exp_f32_e32 v123, v178
	v_cmp_lt_f32_e32 vcc, s51, v142
	s_nop 1
	v_cndmask_b32_e32 v123, 0, v123, vcc
	v_add_f32_e32 v127, v123, v125
	v_exp_f32_e32 v125, v177
	v_cmp_lt_f32_e32 vcc, s51, v143
	s_nop 1
	v_cndmask_b32_e32 v125, 0, v125, vcc
	v_add_f32_e32 v131, v125, v127
	v_exp_f32_e32 v127, v176
	v_cmp_lt_f32_e32 vcc, s51, v144
	s_nop 1
	v_cndmask_b32_e32 v127, 0, v127, vcc
	v_add_f32_e32 v132, v127, v131
	v_exp_f32_e32 v131, v130
	v_cmp_lt_f32_e32 vcc, s51, v145
	s_nop 1
	v_cndmask_b32_e32 v131, 0, v131, vcc
	v_cmp_lt_f32_e32 vcc, s51, v146
	v_add_f32_e32 v132, v131, v132
	s_nop 0
	v_cndmask_b32_e32 v187, 0, v133, vcc
	v_exp_f32_e32 v133, v117
	v_cmp_lt_f32_e32 vcc, s51, v147
	v_add_f32_e32 v132, v187, v132
	s_nop 0
	v_cndmask_b32_e32 v219, 0, v133, vcc
	v_exp_f32_e32 v133, v116
	v_cmp_lt_f32_e32 vcc, s51, v138
	v_add_f32_e32 v132, v219, v132
	s_nop 0
	v_cndmask_b32_e32 v236, 0, v133, vcc
	v_add_f32_e32 v237, v236, v132
